# side-job cache conversion: coalesced source reads + 4 pieces in flight
# baseline (speedup 1.0000x reference)
; DEVI u32x4 pack8(const f32x4 a, const f32x4 b) { u32x4 w; w.x = cvtpk(a[0], a[1]); w.y = cvtpk(a[2], a[3]); w.z = cvtpk(b[0], b[1]); w.w = cvtpk(b[2], b[3]); return w; }
; DEVI const float* IN(int i) { return *(const float* const __attribute__((address_space(4)))*)(kargs() + 8 * i); }
; DEVI void prologue(int wv, LAS unsigned char* lds) {
;     ...
;     {
;         const float* cache_ckv = IN(2); bf16_t* ckvb = (bf16_t*)(ws + O_CKVB);
;         for (size_t i = gt; i < (size_t)2 * MC * 256 / 8; i += 8 * NGT) {
;             f32x4 a[8], b[8];
; #pragma unroll
;             for (int k = 0; k < 8; ++k) { const size_t ii = i + k * NGT; if (ii < (size_t)2 * MC * 256 / 8) { a[k] = *(const f32x4*)(cache_ckv + ii * 8); b[k] = *(const f32x4*)(cache_ckv + ii * 8 + 4); } }
; #pragma unroll
;             for (int k = 0; k < 8; ++k) { const size_t ii = i + k * NGT; if (ii < (size_t)2 * MC * 256 / 8) *(u32x4*)(ckvb + ii * 8) = pack8(a[k], b[k]); }
;         }
;     }
.Lsjd_loop1_1:
	v_mov_b32_e32 v1, v0
	v_cmp_gt_u32_e64 s[12:13], s10, v1
	v_add_u32_e32 v2, 0xcc00, v0
	v_cmp_gt_u32_e64 s[14:15], s10, v2
	v_add_u32_e32 v3, 0x19800, v0
	v_cmp_gt_u32_e64 s[16:17], s10, v3
	v_add_u32_e32 v4, 0x26400, v0
	v_cmp_gt_u32_e64 s[18:19], s10, v4
	s_mov_b64 exec, s[12:13]
	v_lshlrev_b32_e32 v9, 5, v1
	global_load_dwordx4 v[24:27], v9, s[6:7]
	global_load_dwordx4 v[28:31], v9, s[6:7] offset:16
	s_mov_b64 exec, s[14:15]
	v_lshlrev_b32_e32 v10, 5, v2
	global_load_dwordx4 v[32:35], v10, s[6:7]
	global_load_dwordx4 v[36:39], v10, s[6:7] offset:16
	s_mov_b64 exec, s[16:17]
	v_lshlrev_b32_e32 v11, 5, v3
	global_load_dwordx4 v[40:43], v11, s[6:7]
	global_load_dwordx4 v[44:47], v11, s[6:7] offset:16
	s_mov_b64 exec, s[18:19]
	v_lshlrev_b32_e32 v12, 5, v4
	global_load_dwordx4 v[48:51], v12, s[6:7]
	global_load_dwordx4 v[52:55], v12, s[6:7] offset:16
	s_mov_b64 exec, s[12:13]
	v_and_b32_e32 v20, 0x3ff, v1
	v_and_b32_e32 v21, 0xfffffc00, v1
	v_lshrrev_b32_e32 v22, 5, v20
	v_or_b32_e32 v21, v21, v22
	v_bfe_u32 v22, v20, 3, 2
	v_lshl_or_b32 v21, v22, 8, v21
	v_bfe_u32 v22, v20, 2, 1
	v_lshl_or_b32 v21, v22, 5, v21
	v_and_b32_e32 v22, 3, v20
	v_lshl_or_b32 v21, v22, 6, v21
	s_waitcnt vmcnt(6)
	v_cvt_pk_bf16_f32 v100, v24, v25
	v_cvt_pk_bf16_f32 v101, v26, v27
	v_cvt_pk_bf16_f32 v102, v28, v29
	v_cvt_pk_bf16_f32 v103, v30, v31
	v_lshlrev_b32_e32 v104, 4, v21
	global_store_dwordx4 v104, v[100:103], s[8:9]
	s_mov_b64 exec, s[14:15]
	v_and_b32_e32 v20, 0x3ff, v2
	v_and_b32_e32 v21, 0xfffffc00, v2
	v_lshrrev_b32_e32 v22, 5, v20
	v_or_b32_e32 v21, v21, v22
	v_bfe_u32 v22, v20, 3, 2
	v_lshl_or_b32 v21, v22, 8, v21
	v_bfe_u32 v22, v20, 2, 1
	v_lshl_or_b32 v21, v22, 5, v21
	v_and_b32_e32 v22, 3, v20
	v_lshl_or_b32 v21, v22, 6, v21
	s_waitcnt vmcnt(4)
	v_cvt_pk_bf16_f32 v106, v32, v33
	v_cvt_pk_bf16_f32 v107, v34, v35
	v_cvt_pk_bf16_f32 v108, v36, v37
	v_cvt_pk_bf16_f32 v109, v38, v39
	v_lshlrev_b32_e32 v110, 4, v21
	global_store_dwordx4 v110, v[106:109], s[8:9]
	s_mov_b64 exec, s[16:17]
	v_and_b32_e32 v20, 0x3ff, v3
	v_and_b32_e32 v21, 0xfffffc00, v3
	v_lshrrev_b32_e32 v22, 5, v20
	v_or_b32_e32 v21, v21, v22
	v_bfe_u32 v22, v20, 3, 2
	v_lshl_or_b32 v21, v22, 8, v21
	v_bfe_u32 v22, v20, 2, 1
	v_lshl_or_b32 v21, v22, 5, v21
	v_and_b32_e32 v22, 3, v20
	v_lshl_or_b32 v21, v22, 6, v21
	s_waitcnt vmcnt(2)
	v_cvt_pk_bf16_f32 v100, v40, v41
	v_cvt_pk_bf16_f32 v101, v42, v43
	v_cvt_pk_bf16_f32 v102, v44, v45
	v_cvt_pk_bf16_f32 v103, v46, v47
	v_lshlrev_b32_e32 v104, 4, v21
	global_store_dwordx4 v104, v[100:103], s[8:9]
	s_mov_b64 exec, s[18:19]
	v_and_b32_e32 v20, 0x3ff, v4
	v_and_b32_e32 v21, 0xfffffc00, v4
	v_lshrrev_b32_e32 v22, 5, v20
	v_or_b32_e32 v21, v21, v22
	v_bfe_u32 v22, v20, 3, 2
	v_lshl_or_b32 v21, v22, 8, v21
	v_bfe_u32 v22, v20, 2, 1
	v_lshl_or_b32 v21, v22, 5, v21
	v_and_b32_e32 v22, 3, v20
	v_lshl_or_b32 v21, v22, 6, v21
	s_waitcnt vmcnt(0)
	v_cvt_pk_bf16_f32 v106, v48, v49
	v_cvt_pk_bf16_f32 v107, v50, v51
	v_cvt_pk_bf16_f32 v108, v52, v53
	v_cvt_pk_bf16_f32 v109, v54, v55
	v_lshlrev_b32_e32 v110, 4, v21
	global_store_dwordx4 v110, v[106:109], s[8:9]
	s_mov_b64 exec, -1
	v_add_u32_e32 v0, 0x33000, v0
	v_cmp_gt_u32_e32 vcc, s10, v0
	s_and_b64 vcc, exec, vcc
	s_cbranch_scc1 .Lsjd_loop1_1

; DEVI u32x4 pack8(const f32x4 a, const f32x4 b) { u32x4 w; w.x = cvtpk(a[0], a[1]); w.y = cvtpk(a[2], a[3]); w.z = cvtpk(b[0], b[1]); w.w = cvtpk(b[2], b[3]); return w; }
; DEVI const float* IN(int i) { return *(const float* const __attribute__((address_space(4)))*)(kargs() + 8 * i); }
; DEVI void prologue(int wv, LAS unsigned char* lds) {
;     ...
;     {
;         const float* cache_ckv = IN(2); bf16_t* ckvb = (bf16_t*)(ws + O_CKVB);
;         for (size_t i = gt; i < (size_t)2 * MC * 256 / 8; i += 8 * NGT) {
;             f32x4 a[8], b[8];
; #pragma unroll
;             for (int k = 0; k < 8; ++k) { const size_t ii = i + k * NGT; if (ii < (size_t)2 * MC * 256 / 8) { a[k] = *(const f32x4*)(cache_ckv + ii * 8); b[k] = *(const f32x4*)(cache_ckv + ii * 8 + 4); } }
; #pragma unroll
;             for (int k = 0; k < 8; ++k) { const size_t ii = i + k * NGT; if (ii < (size_t)2 * MC * 256 / 8) *(u32x4*)(ckvb + ii * 8) = pack8(a[k], b[k]); }
;         }
;     }
.Lsjd_loop4_0:
	v_mov_b32_e32 v1, v0
	v_cmp_gt_u32_e64 s[12:13], s10, v1
	v_add_u32_e32 v2, 0x1f000, v0
	v_cmp_gt_u32_e64 s[14:15], s10, v2
	v_add_u32_e32 v3, 0x3e000, v0
	v_cmp_gt_u32_e64 s[16:17], s10, v3
	v_add_u32_e32 v4, 0x5d000, v0
	v_cmp_gt_u32_e64 s[18:19], s10, v4
	s_mov_b64 exec, s[12:13]
	v_lshlrev_b32_e32 v9, 5, v1
	global_load_dwordx4 v[24:27], v9, s[6:7]
	global_load_dwordx4 v[28:31], v9, s[6:7] offset:16
	s_mov_b64 exec, s[14:15]
	v_lshlrev_b32_e32 v10, 5, v2
	global_load_dwordx4 v[32:35], v10, s[6:7]
	global_load_dwordx4 v[36:39], v10, s[6:7] offset:16
	s_mov_b64 exec, s[16:17]
	v_lshlrev_b32_e32 v11, 5, v3
	global_load_dwordx4 v[40:43], v11, s[6:7]
	global_load_dwordx4 v[44:47], v11, s[6:7] offset:16
	s_mov_b64 exec, s[18:19]
	v_lshlrev_b32_e32 v12, 5, v4
	global_load_dwordx4 v[48:51], v12, s[6:7]
	global_load_dwordx4 v[52:55], v12, s[6:7] offset:16
	s_mov_b64 exec, s[12:13]
	v_and_b32_e32 v20, 0x3ff, v1
	v_and_b32_e32 v21, 0xfffffc00, v1
	v_lshrrev_b32_e32 v22, 5, v20
	v_or_b32_e32 v21, v21, v22
	v_bfe_u32 v22, v20, 3, 2
	v_lshl_or_b32 v21, v22, 8, v21
	v_bfe_u32 v22, v20, 2, 1
	v_lshl_or_b32 v21, v22, 5, v21
	v_and_b32_e32 v22, 3, v20
	v_lshl_or_b32 v21, v22, 6, v21
	s_waitcnt vmcnt(6)
	v_cvt_pk_bf16_f32 v100, v24, v25
	v_cvt_pk_bf16_f32 v101, v26, v27
	v_cvt_pk_bf16_f32 v102, v28, v29
	v_cvt_pk_bf16_f32 v103, v30, v31
	v_lshlrev_b32_e32 v104, 4, v21
	global_store_dwordx4 v104, v[100:103], s[8:9]
	s_mov_b64 exec, s[14:15]
	v_and_b32_e32 v20, 0x3ff, v2
	v_and_b32_e32 v21, 0xfffffc00, v2
	v_lshrrev_b32_e32 v22, 5, v20
	v_or_b32_e32 v21, v21, v22
	v_bfe_u32 v22, v20, 3, 2
	v_lshl_or_b32 v21, v22, 8, v21
	v_bfe_u32 v22, v20, 2, 1
	v_lshl_or_b32 v21, v22, 5, v21
	v_and_b32_e32 v22, 3, v20
	v_lshl_or_b32 v21, v22, 6, v21
	s_waitcnt vmcnt(4)
	v_cvt_pk_bf16_f32 v106, v32, v33
	v_cvt_pk_bf16_f32 v107, v34, v35
	v_cvt_pk_bf16_f32 v108, v36, v37
	v_cvt_pk_bf16_f32 v109, v38, v39
	v_lshlrev_b32_e32 v110, 4, v21
	global_store_dwordx4 v110, v[106:109], s[8:9]
	s_mov_b64 exec, s[16:17]
	v_and_b32_e32 v20, 0x3ff, v3
	v_and_b32_e32 v21, 0xfffffc00, v3
	v_lshrrev_b32_e32 v22, 5, v20
	v_or_b32_e32 v21, v21, v22
	v_bfe_u32 v22, v20, 3, 2
	v_lshl_or_b32 v21, v22, 8, v21
	v_bfe_u32 v22, v20, 2, 1
	v_lshl_or_b32 v21, v22, 5, v21
	v_and_b32_e32 v22, 3, v20
	v_lshl_or_b32 v21, v22, 6, v21
	s_waitcnt vmcnt(2)
	v_cvt_pk_bf16_f32 v100, v40, v41
	v_cvt_pk_bf16_f32 v101, v42, v43
	v_cvt_pk_bf16_f32 v102, v44, v45
	v_cvt_pk_bf16_f32 v103, v46, v47
	v_lshlrev_b32_e32 v104, 4, v21
	global_store_dwordx4 v104, v[100:103], s[8:9]
	s_mov_b64 exec, s[18:19]
	v_and_b32_e32 v20, 0x3ff, v4
	v_and_b32_e32 v21, 0xfffffc00, v4
	v_lshrrev_b32_e32 v22, 5, v20
	v_or_b32_e32 v21, v21, v22
	v_bfe_u32 v22, v20, 3, 2
	v_lshl_or_b32 v21, v22, 8, v21
	v_bfe_u32 v22, v20, 2, 1
	v_lshl_or_b32 v21, v22, 5, v21
	v_and_b32_e32 v22, 3, v20
	v_lshl_or_b32 v21, v22, 6, v21
	s_waitcnt vmcnt(0)
	v_cvt_pk_bf16_f32 v106, v48, v49
	v_cvt_pk_bf16_f32 v107, v50, v51
	v_cvt_pk_bf16_f32 v108, v52, v53
	v_cvt_pk_bf16_f32 v109, v54, v55
	v_lshlrev_b32_e32 v110, 4, v21
	global_store_dwordx4 v110, v[106:109], s[8:9]
	s_mov_b64 exec, -1
	v_add_u32_e32 v0, 0x7c000, v0
	v_cmp_gt_u32_e32 vcc, s10, v0
	s_and_b64 vcc, exec, vcc
	s_cbranch_scc1 .Lsjd_loop4_0

; DEVI u32x4 pack8(const f32x4 a, const f32x4 b) { u32x4 w; w.x = cvtpk(a[0], a[1]); w.y = cvtpk(a[2], a[3]); w.z = cvtpk(b[0], b[1]); w.w = cvtpk(b[2], b[3]); return w; }
; DEVI const float* IN(int i) { return *(const float* const __attribute__((address_space(4)))*)(kargs() + 8 * i); }
; DEVI void prologue(int wv, LAS unsigned char* lds) {
;     ...
;     {
;         const float* cache_ckv = IN(2); bf16_t* ckvb = (bf16_t*)(ws + O_CKVB);
;         for (size_t i = gt; i < (size_t)2 * MC * 256 / 8; i += 8 * NGT) {
;             f32x4 a[8], b[8];
; #pragma unroll
;             for (int k = 0; k < 8; ++k) { const size_t ii = i + k * NGT; if (ii < (size_t)2 * MC * 256 / 8) { a[k] = *(const f32x4*)(cache_ckv + ii * 8); b[k] = *(const f32x4*)(cache_ckv + ii * 8 + 4); } }
; #pragma unroll
;             for (int k = 0; k < 8; ++k) { const size_t ii = i + k * NGT; if (ii < (size_t)2 * MC * 256 / 8) *(u32x4*)(ckvb + ii * 8) = pack8(a[k], b[k]); }
;         }
;     }
.Lsjd_loop6_0:
	v_mov_b32_e32 v1, v0
	v_cmp_gt_u32_e64 s[12:13], s10, v1
	v_add_u32_e32 v2, 0x1c000, v0
	v_cmp_gt_u32_e64 s[14:15], s10, v2
	v_add_u32_e32 v3, 0x38000, v0
	v_cmp_gt_u32_e64 s[16:17], s10, v3
	v_add_u32_e32 v4, 0x54000, v0
	v_cmp_gt_u32_e64 s[18:19], s10, v4
	s_mov_b64 exec, s[12:13]
	v_lshlrev_b32_e32 v9, 5, v1
	global_load_dwordx4 v[24:27], v9, s[6:7]
	global_load_dwordx4 v[28:31], v9, s[6:7] offset:16
	s_mov_b64 exec, s[14:15]
	v_lshlrev_b32_e32 v10, 5, v2
	global_load_dwordx4 v[32:35], v10, s[6:7]
	global_load_dwordx4 v[36:39], v10, s[6:7] offset:16
	s_mov_b64 exec, s[16:17]
	v_lshlrev_b32_e32 v11, 5, v3
	global_load_dwordx4 v[40:43], v11, s[6:7]
	global_load_dwordx4 v[44:47], v11, s[6:7] offset:16
	s_mov_b64 exec, s[18:19]
	v_lshlrev_b32_e32 v12, 5, v4
	global_load_dwordx4 v[48:51], v12, s[6:7]
	global_load_dwordx4 v[52:55], v12, s[6:7] offset:16
	s_mov_b64 exec, s[12:13]
	v_and_b32_e32 v20, 0x3ff, v1
	v_and_b32_e32 v21, 0xfffffc00, v1
	v_lshrrev_b32_e32 v22, 5, v20
	v_or_b32_e32 v21, v21, v22
	v_bfe_u32 v22, v20, 3, 2
	v_lshl_or_b32 v21, v22, 8, v21
	v_bfe_u32 v22, v20, 2, 1
	v_lshl_or_b32 v21, v22, 5, v21
	v_and_b32_e32 v22, 3, v20
	v_lshl_or_b32 v21, v22, 6, v21
	s_waitcnt vmcnt(6)
	v_cvt_pk_bf16_f32 v100, v24, v25
	v_cvt_pk_bf16_f32 v101, v26, v27
	v_cvt_pk_bf16_f32 v102, v28, v29
	v_cvt_pk_bf16_f32 v103, v30, v31
	v_lshlrev_b32_e32 v104, 4, v21
	global_store_dwordx4 v104, v[100:103], s[8:9]
	s_mov_b64 exec, s[14:15]
	v_and_b32_e32 v20, 0x3ff, v2
	v_and_b32_e32 v21, 0xfffffc00, v2
	v_lshrrev_b32_e32 v22, 5, v20
	v_or_b32_e32 v21, v21, v22
	v_bfe_u32 v22, v20, 3, 2
	v_lshl_or_b32 v21, v22, 8, v21
	v_bfe_u32 v22, v20, 2, 1
	v_lshl_or_b32 v21, v22, 5, v21
	v_and_b32_e32 v22, 3, v20
	v_lshl_or_b32 v21, v22, 6, v21
	s_waitcnt vmcnt(4)
	v_cvt_pk_bf16_f32 v106, v32, v33
	v_cvt_pk_bf16_f32 v107, v34, v35
	v_cvt_pk_bf16_f32 v108, v36, v37
	v_cvt_pk_bf16_f32 v109, v38, v39
	v_lshlrev_b32_e32 v110, 4, v21
	global_store_dwordx4 v110, v[106:109], s[8:9]
	s_mov_b64 exec, s[16:17]
	v_and_b32_e32 v20, 0x3ff, v3
	v_and_b32_e32 v21, 0xfffffc00, v3
	v_lshrrev_b32_e32 v22, 5, v20
	v_or_b32_e32 v21, v21, v22
	v_bfe_u32 v22, v20, 3, 2
	v_lshl_or_b32 v21, v22, 8, v21
	v_bfe_u32 v22, v20, 2, 1
	v_lshl_or_b32 v21, v22, 5, v21
	v_and_b32_e32 v22, 3, v20
	v_lshl_or_b32 v21, v22, 6, v21
	s_waitcnt vmcnt(2)
	v_cvt_pk_bf16_f32 v100, v40, v41
	v_cvt_pk_bf16_f32 v101, v42, v43
	v_cvt_pk_bf16_f32 v102, v44, v45
	v_cvt_pk_bf16_f32 v103, v46, v47
	v_lshlrev_b32_e32 v104, 4, v21
	global_store_dwordx4 v104, v[100:103], s[8:9]
	s_mov_b64 exec, s[18:19]
	v_and_b32_e32 v20, 0x3ff, v4
	v_and_b32_e32 v21, 0xfffffc00, v4
	v_lshrrev_b32_e32 v22, 5, v20
	v_or_b32_e32 v21, v21, v22
	v_bfe_u32 v22, v20, 3, 2
	v_lshl_or_b32 v21, v22, 8, v21
	v_bfe_u32 v22, v20, 2, 1
	v_lshl_or_b32 v21, v22, 5, v21
	v_and_b32_e32 v22, 3, v20
	v_lshl_or_b32 v21, v22, 6, v21
	s_waitcnt vmcnt(0)
	v_cvt_pk_bf16_f32 v106, v48, v49
	v_cvt_pk_bf16_f32 v107, v50, v51
	v_cvt_pk_bf16_f32 v108, v52, v53
	v_cvt_pk_bf16_f32 v109, v54, v55
	v_lshlrev_b32_e32 v110, 4, v21
	global_store_dwordx4 v110, v[106:109], s[8:9]
	s_mov_b64 exec, -1
	v_add_u32_e32 v0, 0x70000, v0
	v_cmp_gt_u32_e32 vcc, s10, v0
	s_and_b64 vcc, exec, vcc
	s_cbranch_scc1 .Lsjd_loop6_0
